# NSA window pass (mode 3): unmasked middle tile pairs take the lean iteration (C operand = -m for both tiles), same path as the selected pass
# baseline (speedup 1.0000x reference)
.LBB0_1463:
	s_cmp_lt_u32 s63, 2
	s_cbranch_scc1 .Lm2_no
	s_add_i32 s98, s54, 1
	s_cmp_ge_i32 s98, s53
	s_cbranch_scc1 .Lm2_no
	v_cmp_eq_f32_e64 s[18:19], s73, v222
	s_cmp_lg_u64 s[18:19], 0
	s_cbranch_scc1 .Lm2_no
.Lm2_head:
	s_add_i32 s21, s38, s45
	s_and_b32 s20, s45, 2
	s_add_i32 s54, s54, 1
	s_mov_b64 s[94:95], 0
	s_lshl_b32 s30, s20, 13
	v_add_u32_e32 v8, s30, v169
	ds_read_b128 v[10:13], v8
	ds_read_b128 v[14:17], v8 offset:512
	ds_read_b128 v[174:177], v8 offset:2048
	ds_read_b128 v[178:181], v8 offset:2560
	ds_read_b128 v[182:185], v8 offset:4096
	ds_read_b128 v[186:189], v8 offset:4608
	ds_read_b128 v[228:231], v8 offset:6144
	ds_read_b128 v[232:235], v8 offset:6656
	v_add_u32_e32 v3, s30, v193
	s_cmp_eq_u32 s63, 3
	s_cbranch_scc1 .Lm3_head
	s_lshr_b32 s0, s21, 5
	s_cmp_lt_u32 s0, 2
	s_cselect_b64 s[98:99], -1, 0
	s_bitcmp1_b32 s0, 0
	s_cselect_b64 s[0:1], -1, 0
	s_and_b32 s28, s21, 31
	v_cndmask_b32_e64 v5, v130, v131, s[0:1]
	v_cndmask_b32_e64 v6, v132, v133, s[0:1]
	v_cndmask_b32_e64 v5, v6, v5, s[98:99]
	v_lshrrev_b32_e32 v5, s28, v5
	v_and_b32_e32 v6, 1, v5
	v_bfe_u32 v9, v5, 1, 1
	v_xor_b32_e32 v7, 0x80000000, v222
	v_cmp_eq_u32_e32 vcc, 1, v6
	v_cmp_eq_u32_e64 s[98:99], 1, v9
	v_add_f32_e32 v4, v7, v201
	s_cmp_lg_u64 vcc, 0
	s_cselect_b32 s55, 1, 0
	v_cndmask_b32_e32 v82, v4, v7, vcc
	v_cndmask_b32_e64 v50, v4, v7, s[98:99]
	s_cmp_lg_u64 s[98:99], 0
	s_cselect_b32 s0, 2, 0
	s_or_b32 s55, s55, s0
	s_cmp_eq_u32 s55, 3
	s_cbranch_scc0 .Lm2_partial
.Lm2_fullbody:
	v_mov_b32_e32 v83, v82
	v_mov_b64_e32 v[84:85], v[82:83]
	v_mov_b64_e32 v[86:87], v[82:83]
	v_mov_b64_e32 v[88:89], v[82:83]
	v_mov_b64_e32 v[90:91], v[82:83]
	v_mov_b64_e32 v[92:93], v[82:83]
	v_mov_b64_e32 v[94:95], v[82:83]
	v_mov_b64_e32 v[96:97], v[82:83]
	v_mov_b32_e32 v51, v50
	v_mov_b64_e32 v[52:53], v[50:51]
	s_waitcnt lgkmcnt(7)
	v_mfma_f32_32x32x16_bf16 v[98:113], v[10:13], v[114:117], v[82:97]
	ds_read_b128 v[10:13], v8 offset:8192
	v_mov_b64_e32 v[54:55], v[50:51]
	v_mov_b64_e32 v[56:57], v[50:51]
	v_mov_b64_e32 v[58:59], v[50:51]
	v_mov_b64_e32 v[60:61], v[50:51]
	v_mov_b64_e32 v[62:63], v[50:51]
	s_waitcnt lgkmcnt(7)
	v_mfma_f32_32x32x16_bf16 v[82:97], v[14:17], v[114:117], v[82:97]
	ds_read_b128 v[14:17], v8 offset:8704
	v_mov_b64_e32 v[64:65], v[50:51]
	s_add_i32 s0, s21, 2
	s_ashr_i32 s1, s0, 31
	s_lshl_b64 s[0:1], s[0:1], 6
	s_add_u32 s0, s0, s84
	s_waitcnt lgkmcnt(7)
	v_mfma_f32_32x32x16_bf16 v[98:113], v[174:177], v[118:121], v[98:113]
	ds_read_b128 v[174:177], v8 offset:10240
	s_addc_u32 s1, s1, s85
	s_lshl_b64 s[0:1], s[0:1], 7
	s_add_u32 s28, s86, s0
	s_addc_u32 s29, s87, s1
	s_sub_i32 s31, s37, s30
	s_waitcnt lgkmcnt(7)
	v_mfma_f32_32x32x16_bf16 v[82:97], v[178:181], v[118:121], v[82:97]
	ds_read_b128 v[178:181], v8 offset:10752
	s_add_i32 s31, s31, 0x4000
	v_lshlrev_b32_e32 v5, 7, v138
	s_mov_b32 m0, s31
	s_movk_i32 s30, 0x80
	global_load_lds_dwordx4 v5, s[28:29]
	s_waitcnt lgkmcnt(7)
	v_mfma_f32_32x32x16_bf16 v[98:113], v[182:185], v[122:125], v[98:113]
	ds_read_b128 v[182:185], v8 offset:12288
	v_mad_u64_u32 v[226:227], vcc, v168, s30, v[134:135]
	s_add_i32 s31, s31, 0x8000
	v_lshl_add_u64 v[6:7], v[226:227], 0, s[0:1]
	s_mov_b32 m0, s31
	s_cmp_lt_i32 s45, s44
	s_waitcnt lgkmcnt(7)
	v_mfma_f32_32x32x16_bf16 v[82:97], v[186:189], v[122:125], v[82:97]
	ds_read_b128 v[186:189], v8 offset:12800
	global_load_lds_dwordx4 v[6:7], off
	s_cselect_b32 s98, 0x2000, 0
	s_add_u32 s28, s28, s98
	s_waitcnt lgkmcnt(7)
	v_mfma_f32_32x32x16_bf16 v[98:113], v[228:231], v[126:129], v[98:113]
	ds_read_b128 v[228:231], v8 offset:14336
	s_addc_u32 s29, s29, 0
	s_add_u32 s0, s0, s98
	s_addc_u32 s1, s1, 0
	s_sub_i32 s31, s31, 0x6000
	s_mov_b32 m0, s31
	s_waitcnt lgkmcnt(7)
	v_mfma_f32_32x32x16_bf16 v[82:97], v[232:235], v[126:129], v[82:97]
	ds_read_b128 v[232:235], v8 offset:14848
	v_lshl_add_u64 v[6:7], v[226:227], 0, s[0:1]
	global_load_lds_dwordx4 v5, s[28:29]
	s_add_i32 s31, s31, 0x8000
	s_waitcnt lgkmcnt(7)
	v_mfma_f32_32x32x16_bf16 v[66:81], v[10:13], v[114:117], v[50:65]
	ds_read_b64_tr_b16 v[10:11], v3 offset:32768
	ds_read_b64_tr_b16 v[12:13], v3 offset:33280
	s_mov_b32 m0, s31
	s_nop 0
	global_load_lds_dwordx4 v[6:7], off
	s_waitcnt lgkmcnt(8)
	v_mfma_f32_32x32x16_bf16 v[50:65], v[14:17], v[114:117], v[50:65]
	ds_read_b64_tr_b16 v[14:15], v3 offset:36864
	ds_read_b64_tr_b16 v[16:17], v3 offset:37376
	v_exp_f32_e32 v98, v98
	v_exp_f32_e32 v99, v99
	v_exp_f32_e32 v100, v100
	s_waitcnt lgkmcnt(9)
	v_mfma_f32_32x32x16_bf16 v[66:81], v[174:177], v[118:121], v[66:81]
	ds_read_b64_tr_b16 v[174:175], v3 offset:33792
	ds_read_b64_tr_b16 v[176:177], v3 offset:34304
	v_exp_f32_e32 v101, v101
	v_exp_f32_e32 v102, v102
	v_exp_f32_e32 v103, v103
	s_waitcnt lgkmcnt(10)
	v_mfma_f32_32x32x16_bf16 v[50:65], v[178:181], v[118:121], v[50:65]
	ds_read_b64_tr_b16 v[178:179], v3 offset:37888
	ds_read_b64_tr_b16 v[180:181], v3 offset:38400
	v_exp_f32_e32 v104, v104
	v_exp_f32_e32 v105, v105
	v_cvt_pk_bf16_f32 v236, v98, v99
	s_waitcnt lgkmcnt(11)
	v_mfma_f32_32x32x16_bf16 v[66:81], v[182:185], v[122:125], v[66:81]
	ds_read_b64_tr_b16 v[182:183], v3 offset:34816
	ds_read_b64_tr_b16 v[184:185], v3 offset:35328
	v_cvt_pk_bf16_f32 v237, v100, v101
	v_cvt_pk_bf16_f32 v238, v102, v103
	v_cvt_pk_bf16_f32 v239, v104, v105
	v_exp_f32_e32 v106, v106
	s_waitcnt lgkmcnt(12)
	v_mfma_f32_32x32x16_bf16 v[50:65], v[186:189], v[122:125], v[50:65]
	ds_read_b64_tr_b16 v[186:187], v3 offset:38912
	ds_read_b64_tr_b16 v[188:189], v3 offset:39424
	v_exp_f32_e32 v107, v107
	v_exp_f32_e32 v108, v108
	v_exp_f32_e32 v109, v109
	s_waitcnt lgkmcnt(13)
	v_mfma_f32_32x32x16_bf16 v[66:81], v[228:231], v[126:129], v[66:81]
	ds_read_b64_tr_b16 v[228:229], v3 offset:35840
	ds_read_b64_tr_b16 v[230:231], v3 offset:36352
	v_exp_f32_e32 v110, v110
	v_exp_f32_e32 v111, v111
	v_exp_f32_e32 v112, v112
	s_waitcnt lgkmcnt(14)
	v_mfma_f32_32x32x16_bf16 v[50:65], v[232:235], v[126:129], v[50:65]
	s_waitcnt lgkmcnt(13)
	ds_read_b64_tr_b16 v[232:233], v3 offset:39936
	ds_read_b64_tr_b16 v[234:235], v3 offset:40448
	v_exp_f32_e32 v113, v113
	v_cvt_pk_bf16_f32 v240, v106, v107
	v_cvt_pk_bf16_f32 v241, v108, v109
	v_cvt_pk_bf16_f32 v242, v110, v111
	s_waitcnt lgkmcnt(14)
	v_mfma_f32_32x32x16_bf16 v[34:49], v[236:239], v[10:13], v[34:49]
	s_waitcnt lgkmcnt(13)
	ds_read_b64_tr_b16 v[10:11], v3 offset:40960
	ds_read_b64_tr_b16 v[12:13], v3 offset:41472
	v_cvt_pk_bf16_f32 v243, v112, v113
	v_exp_f32_e32 v82, v82
	v_exp_f32_e32 v83, v83
	s_waitcnt lgkmcnt(14)
	v_mfma_f32_32x32x16_bf16 v[18:33], v[236:239], v[14:17], v[18:33]
	s_waitcnt lgkmcnt(13)
	ds_read_b64_tr_b16 v[14:15], v3 offset:45056
	ds_read_b64_tr_b16 v[16:17], v3 offset:45568
	v_exp_f32_e32 v84, v84
	v_exp_f32_e32 v85, v85
	v_exp_f32_e32 v86, v86
	s_waitcnt lgkmcnt(14)
	v_mfma_f32_32x32x16_bf16 v[34:49], v[240:243], v[174:177], v[34:49]
	s_waitcnt lgkmcnt(13)
	ds_read_b64_tr_b16 v[174:175], v3 offset:41984
	ds_read_b64_tr_b16 v[176:177], v3 offset:42496
	v_exp_f32_e32 v87, v87
	v_exp_f32_e32 v88, v88
	v_exp_f32_e32 v89, v89
	s_waitcnt lgkmcnt(14)
	v_mfma_f32_32x32x16_bf16 v[18:33], v[240:243], v[178:181], v[18:33]
	s_waitcnt lgkmcnt(13)
	ds_read_b64_tr_b16 v[178:179], v3 offset:46080
	ds_read_b64_tr_b16 v[180:181], v3 offset:46592
	v_cvt_pk_bf16_f32 v244, v82, v83
	v_cvt_pk_bf16_f32 v245, v84, v85
	v_cvt_pk_bf16_f32 v246, v86, v87
	v_cvt_pk_bf16_f32 v247, v88, v89
	v_exp_f32_e32 v90, v90
	v_exp_f32_e32 v91, v91
	s_waitcnt lgkmcnt(14)
	v_mfma_f32_32x32x16_bf16 v[34:49], v[244:247], v[182:185], v[34:49]
	s_waitcnt lgkmcnt(13)
	ds_read_b64_tr_b16 v[182:183], v3 offset:43008
	ds_read_b64_tr_b16 v[184:185], v3 offset:43520
	v_exp_f32_e32 v92, v92
	v_exp_f32_e32 v93, v93
	v_exp_f32_e32 v94, v94
	s_waitcnt lgkmcnt(14)
	v_mfma_f32_32x32x16_bf16 v[18:33], v[244:247], v[186:189], v[18:33]
	s_waitcnt lgkmcnt(13)
	ds_read_b64_tr_b16 v[186:187], v3 offset:47104
	ds_read_b64_tr_b16 v[188:189], v3 offset:47616
	v_exp_f32_e32 v95, v95
	v_exp_f32_e32 v96, v96
	v_exp_f32_e32 v97, v97
	v_cvt_pk_bf16_f32 v248, v90, v91
	v_cvt_pk_bf16_f32 v249, v92, v93
	v_cvt_pk_bf16_f32 v250, v94, v95
	v_cvt_pk_bf16_f32 v251, v96, v97
	v_exp_f32_e32 v66, v66
	v_exp_f32_e32 v67, v67
	s_waitcnt lgkmcnt(14)
	v_mfma_f32_32x32x16_bf16 v[34:49], v[248:251], v[228:231], v[34:49]
	s_waitcnt lgkmcnt(13)
	ds_read_b64_tr_b16 v[228:229], v3 offset:44032
	ds_read_b64_tr_b16 v[230:231], v3 offset:44544
	v_exp_f32_e32 v68, v68
	v_exp_f32_e32 v69, v69
	v_exp_f32_e32 v70, v70
	s_waitcnt lgkmcnt(14)
	v_mfma_f32_32x32x16_bf16 v[18:33], v[248:251], v[232:235], v[18:33]
	s_waitcnt lgkmcnt(13)
	ds_read_b64_tr_b16 v[232:233], v3 offset:48128
	ds_read_b64_tr_b16 v[234:235], v3 offset:48640
	v_exp_f32_e32 v71, v71
	v_exp_f32_e32 v72, v72
	v_exp_f32_e32 v73, v73
	v_cvt_pk_bf16_f32 v236, v66, v67
	v_cvt_pk_bf16_f32 v237, v68, v69
	v_cvt_pk_bf16_f32 v238, v70, v71
	v_cvt_pk_bf16_f32 v239, v72, v73
	v_exp_f32_e32 v74, v74
	v_exp_f32_e32 v75, v75
	s_waitcnt lgkmcnt(14)
	v_mfma_f32_32x32x16_bf16 v[34:49], v[236:239], v[10:13], v[34:49]
	v_exp_f32_e32 v76, v76
	v_exp_f32_e32 v77, v77
	v_exp_f32_e32 v78, v78
	s_waitcnt lgkmcnt(12)
	v_mfma_f32_32x32x16_bf16 v[18:33], v[236:239], v[14:17], v[18:33]
	v_exp_f32_e32 v79, v79
	v_exp_f32_e32 v80, v80
	v_exp_f32_e32 v81, v81
	v_cvt_pk_bf16_f32 v240, v74, v75
	v_cvt_pk_bf16_f32 v241, v76, v77
	v_cvt_pk_bf16_f32 v242, v78, v79
	v_cvt_pk_bf16_f32 v243, v80, v81
	v_exp_f32_e32 v50, v50
	v_exp_f32_e32 v51, v51
	s_waitcnt lgkmcnt(10)
	v_mfma_f32_32x32x16_bf16 v[34:49], v[240:243], v[174:177], v[34:49]
	v_exp_f32_e32 v52, v52
	v_exp_f32_e32 v53, v53
	v_exp_f32_e32 v54, v54
	s_waitcnt lgkmcnt(8)
	v_mfma_f32_32x32x16_bf16 v[18:33], v[240:243], v[178:181], v[18:33]
	v_exp_f32_e32 v55, v55
	v_exp_f32_e32 v56, v56
	v_exp_f32_e32 v57, v57
	v_cvt_pk_bf16_f32 v244, v50, v51
	v_cvt_pk_bf16_f32 v245, v52, v53
	v_cvt_pk_bf16_f32 v246, v54, v55
	v_cvt_pk_bf16_f32 v247, v56, v57
	v_exp_f32_e32 v58, v58
	v_exp_f32_e32 v59, v59
	s_waitcnt lgkmcnt(6)
	v_mfma_f32_32x32x16_bf16 v[34:49], v[244:247], v[182:185], v[34:49]
	v_exp_f32_e32 v60, v60
	v_exp_f32_e32 v61, v61
	v_exp_f32_e32 v62, v62
	s_waitcnt lgkmcnt(4)
	v_mfma_f32_32x32x16_bf16 v[18:33], v[244:247], v[186:189], v[18:33]
	v_exp_f32_e32 v63, v63
	v_exp_f32_e32 v64, v64
	v_exp_f32_e32 v65, v65
	v_cvt_pk_bf16_f32 v248, v58, v59
	v_cvt_pk_bf16_f32 v249, v60, v61
	v_cvt_pk_bf16_f32 v250, v62, v63
	v_cvt_pk_bf16_f32 v251, v64, v65
	v_pk_add_f32 v[4:5], v[98:99], v[100:101]
	v_pk_add_f32 v[6:7], v[82:83], v[84:85]
	s_waitcnt lgkmcnt(2)
	v_mfma_f32_32x32x16_bf16 v[34:49], v[248:251], v[228:231], v[34:49]
	v_pk_add_f32 v[4:5], v[4:5], v[102:103]
	v_pk_add_f32 v[6:7], v[6:7], v[86:87]
	v_pk_add_f32 v[4:5], v[4:5], v[104:105]
	v_pk_add_f32 v[6:7], v[6:7], v[88:89]
	v_pk_add_f32 v[4:5], v[4:5], v[106:107]
	s_waitcnt lgkmcnt(0)
	v_mfma_f32_32x32x16_bf16 v[18:33], v[248:251], v[232:235], v[18:33]
	v_pk_add_f32 v[6:7], v[6:7], v[90:91]
	v_pk_add_f32 v[4:5], v[4:5], v[108:109]
	v_pk_add_f32 v[6:7], v[6:7], v[92:93]
	v_pk_add_f32 v[4:5], v[4:5], v[110:111]
	v_pk_add_f32 v[6:7], v[6:7], v[94:95]
	v_pk_add_f32 v[4:5], v[4:5], v[112:113]
	v_pk_add_f32 v[6:7], v[6:7], v[96:97]
	v_add_f32_e32 v6, v6, v7
	v_add_f32_e32 v4, v4, v5
	v_add_f32_e32 v4, v6, v4
	v_mov_b32_e32 v5, v4
	v_add_f32_e32 v225, v225, v4
	v_pk_add_f32 v[4:5], v[66:67], v[68:69]
	v_pk_add_f32 v[6:7], v[50:51], v[52:53]
	v_pk_add_f32 v[4:5], v[4:5], v[70:71]
	v_pk_add_f32 v[6:7], v[6:7], v[54:55]
	v_pk_add_f32 v[4:5], v[4:5], v[72:73]
	v_pk_add_f32 v[6:7], v[6:7], v[56:57]
	v_pk_add_f32 v[4:5], v[4:5], v[74:75]
	v_pk_add_f32 v[6:7], v[6:7], v[58:59]
	v_pk_add_f32 v[4:5], v[4:5], v[76:77]
	v_pk_add_f32 v[6:7], v[6:7], v[60:61]
	v_pk_add_f32 v[4:5], v[4:5], v[78:79]
	v_pk_add_f32 v[6:7], v[6:7], v[62:63]
	v_pk_add_f32 v[4:5], v[4:5], v[80:81]
	v_pk_add_f32 v[6:7], v[6:7], v[64:65]
	v_add_f32_e32 v6, v6, v7
	v_add_f32_e32 v4, v4, v5
	v_add_f32_e32 v4, v6, v4
	v_add_f32_e32 v225, v225, v4
	s_mov_b64 s[20:21], 0
	s_mov_b32 s30, 0x437f0000
	v_cmp_nge_f32_e32 vcc, s30, v5
	v_cmp_nge_f32_e64 s[98:99], s30, v4
	s_or_b64 s[98:99], vcc, s[98:99]
	s_cbranch_scc1 .Lm2_rare_full
	s_waitcnt vmcnt(0) lgkmcnt(0)
	s_barrier
	s_add_i32 s45, s45, 2
	s_add_i32 s98, s54, 1
	s_cmp_lt_i32 s98, s53
	s_cbranch_scc1 .Lm2_head
	s_branch .LBB0_1463
.Lm3_head:
	v_xor_b32_e32 v7, 0x80000000, v222
	s_mov_b32 s55, 3
	v_mov_b32_e32 v82, v7
	v_mov_b32_e32 v50, v7
	s_branch .Lm2_fullbody
